# chunk-state: K/V ushort loads batched and pipelined across ks, unrolled
# baseline (speedup 1.0000x reference)
.LBB0_503:
	s_ashr_i32 s2, s8, 8
	s_bfe_u32 s0, s8, 0x20006
	s_ashr_i32 s3, s2, 31
	s_lshl_b32 s31, s0, 12
	s_lshl_b32 s9, s0, 8
	s_lshl_b64 s[0:1], s[2:3], 12
	s_lshl_b32 s3, s8, 6
	v_mov_b32_e32 v0, v139
	s_and_b32 s3, s3, 0xfc0
	s_or_b32 s0, s0, s3
	v_and_b32_e32 v1, 63, v0
	s_waitcnt lgkmcnt(0)
	v_or_b32_e32 v2, s0, v1
	v_mov_b32_e32 v3, s1
	v_readlane_b32 s0, v255, 8
	v_lshlrev_b64 v[2:3], 5, v[2:3]
	v_readlane_b32 s1, v255, 9
	v_cmp_lt_i32_e64 s[6:7], v177, v176
	s_bfe_u32 s29, s26, 0x60006
	v_lshl_add_u64 v[2:3], s[0:1], 0, v[2:3]
	s_lshr_b32 s0, s8, 4
	s_and_b32 s4, s0, 12
	v_lshl_add_u64 v[4:5], v[2:3], 0, s[4:5]
	global_load_dword v2, v[4:5], off
	global_load_dword v3, v[4:5], off offset:16
	s_mov_b32 s0, 0xb2a5705f
	s_lshl_b32 s3, s2, 14
	s_lshl_b32 s30, s29, 6
	s_or_b32 s3, s3, s31
	s_mul_i32 s29, s29, 0x48000
	v_and_b32_e32 v138, 31, v0
	v_bfe_u32 v186, v0, 5, 1
	v_and_b32_e32 v0, 32, v0
	s_movk_i32 s4, 0x100
	v_and_or_b32 v188, v174, s4, v0
	v_lshlrev_b32_e32 v0, 10, v186
	v_lshlrev_b32_e32 v136, 1, v138
	s_or_b32 s6, s3, s30
	s_ashr_i32 s7, s6, 31
	s_lshl_b64 s[6:7], s[6:7], 7
	s_add_u32 s6, s24, s6
	s_addc_u32 s7, s25, s7
	v_lshlrev_b32_e32 v158, 10, v186
	v_mov_b32_e32 v159, 0
	s_mul_hi_i32 s3, s2, 0x1200000
	s_mul_i32 s2, s2, 0x1200000
	s_add_u32 s2, s2, s29
	s_addc_u32 s3, s3, 0
	v_lshl_add_u64 v[140:141], s[6:7], 0, v[158:159]
	s_add_u32 s4, s82, s9
	s_addc_u32 s6, s83, 0
	s_add_u32 s2, s4, s2
	s_addc_u32 s3, s6, s3
	v_mov_b64_e32 v[160:161], s[2:3]
	s_mov_b32 s2, 0x9000
	v_mad_u64_u32 v[142:143], s[2:3], v186, s2, v[160:161]
	s_mov_b32 s7, 0
	v_lshl_add_u64 v[148:149], v[140:141], 0, v[136:137]
	v_lshl_add_u64 v[146:147], v[142:143], 0, v[136:137]
	global_load_ushort v190, v[148:149], off offset:-2048
	global_load_ushort v192, v[148:149], off offset:-1920
	global_load_ushort v194, v[148:149], off offset:-1792
	global_load_ushort v196, v[148:149], off offset:-1664
	global_load_ushort v198, v[148:149], off offset:-1536
	global_load_ushort v200, v[148:149], off offset:-1408
	global_load_ushort v202, v[148:149], off offset:-1280
	global_load_ushort v204, v[148:149], off offset:-1152
	global_load_ushort v191, v[148:149], off offset:-1984
	global_load_ushort v193, v[148:149], off offset:-1856
	global_load_ushort v195, v[148:149], off offset:-1728
	global_load_ushort v197, v[148:149], off offset:-1600
	global_load_ushort v199, v[148:149], off offset:-1472
	global_load_ushort v201, v[148:149], off offset:-1344
	global_load_ushort v203, v[148:149], off offset:-1216
	global_load_ushort v205, v[148:149], off offset:-1088
	s_mov_b32 s6, 0x7000940
	v_lshl_add_u64 v[162:163], v[146:147], 0, s[6:7]
	global_load_ushort v216, v[162:163], off offset:0
	s_mov_b32 s6, 0x7001b40
	v_lshl_add_u64 v[162:163], v[146:147], 0, s[6:7]
	global_load_ushort v217, v[162:163], off offset:0
	s_mov_b32 s6, 0x7002d40
	v_lshl_add_u64 v[162:163], v[146:147], 0, s[6:7]
	global_load_ushort v218, v[162:163], off offset:0
	s_mov_b32 s6, 0x7003f40
	v_lshl_add_u64 v[162:163], v[146:147], 0, s[6:7]
	global_load_ushort v219, v[162:163], off offset:0
	s_mov_b32 s6, 0x7005140
	v_lshl_add_u64 v[162:163], v[146:147], 0, s[6:7]
	global_load_ushort v220, v[162:163], off offset:0
	s_mov_b32 s6, 0x7006340
	v_lshl_add_u64 v[162:163], v[146:147], 0, s[6:7]
	global_load_ushort v221, v[162:163], off offset:0
	s_mov_b32 s6, 0x7007540
	v_lshl_add_u64 v[162:163], v[146:147], 0, s[6:7]
	global_load_ushort v222, v[162:163], off offset:0
	s_mov_b32 s6, 0x7008740
	v_lshl_add_u64 v[162:163], v[146:147], 0, s[6:7]
	global_load_ushort v223, v[162:163], off offset:0
	s_mov_b32 s6, 0x7000940
	v_lshl_add_u64 v[162:163], v[146:147], 0, s[6:7]
	global_load_ushort v224, v[162:163], off offset:64
	s_mov_b32 s6, 0x7001b40
	v_lshl_add_u64 v[162:163], v[146:147], 0, s[6:7]
	global_load_ushort v225, v[162:163], off offset:64
	s_mov_b32 s6, 0x7002d40
	v_lshl_add_u64 v[162:163], v[146:147], 0, s[6:7]
	global_load_ushort v226, v[162:163], off offset:64
	s_mov_b32 s6, 0x7003f40
	v_lshl_add_u64 v[162:163], v[146:147], 0, s[6:7]
	global_load_ushort v227, v[162:163], off offset:64
	s_mov_b32 s6, 0x7005140
	v_lshl_add_u64 v[162:163], v[146:147], 0, s[6:7]
	global_load_ushort v244, v[162:163], off offset:64
	s_mov_b32 s6, 0x7006340
	v_lshl_add_u64 v[162:163], v[146:147], 0, s[6:7]
	global_load_ushort v245, v[162:163], off offset:64
	s_mov_b32 s6, 0x7007540
	v_lshl_add_u64 v[162:163], v[146:147], 0, s[6:7]
	global_load_ushort v246, v[162:163], off offset:64
	s_mov_b32 s6, 0x7008740
	v_lshl_add_u64 v[162:163], v[146:147], 0, s[6:7]
	global_load_ushort v247, v[162:163], off offset:64
	s_mov_b32 s6, 0x7000940
	v_lshl_add_u64 v[162:163], v[146:147], 0, s[6:7]
	global_load_ushort v248, v[162:163], off offset:128
	s_mov_b32 s6, 0x7001b40
	v_lshl_add_u64 v[162:163], v[146:147], 0, s[6:7]
	global_load_ushort v249, v[162:163], off offset:128
	s_mov_b32 s6, 0x7002d40
	v_lshl_add_u64 v[162:163], v[146:147], 0, s[6:7]
	global_load_ushort v250, v[162:163], off offset:128
	s_mov_b32 s6, 0x7003f40
	v_lshl_add_u64 v[162:163], v[146:147], 0, s[6:7]
	global_load_ushort v251, v[162:163], off offset:128
	s_mov_b32 s6, 0x7005140
	v_lshl_add_u64 v[162:163], v[146:147], 0, s[6:7]
	global_load_ushort v252, v[162:163], off offset:128
	s_mov_b32 s6, 0x7006340
	v_lshl_add_u64 v[162:163], v[146:147], 0, s[6:7]
	global_load_ushort v253, v[162:163], off offset:128
	s_mov_b32 s6, 0x7007540
	v_lshl_add_u64 v[162:163], v[146:147], 0, s[6:7]
	global_load_ushort v153, v[162:163], off offset:128
	s_mov_b32 s6, 0x7008740
	v_lshl_add_u64 v[162:163], v[146:147], 0, s[6:7]
	global_load_ushort v155, v[162:163], off offset:128
	s_mov_b32 s6, 0x7000940
	v_lshl_add_u64 v[162:163], v[146:147], 0, s[6:7]
	global_load_ushort v206, v[162:163], off offset:192
	s_mov_b32 s6, 0x7001b40
	v_lshl_add_u64 v[162:163], v[146:147], 0, s[6:7]
	global_load_ushort v207, v[162:163], off offset:192
	s_mov_b32 s6, 0x7002d40
	v_lshl_add_u64 v[162:163], v[146:147], 0, s[6:7]
	global_load_ushort v208, v[162:163], off offset:192
	s_mov_b32 s6, 0x7003f40
	v_lshl_add_u64 v[162:163], v[146:147], 0, s[6:7]
	global_load_ushort v209, v[162:163], off offset:192
	s_mov_b32 s6, 0x7005140
	v_lshl_add_u64 v[162:163], v[146:147], 0, s[6:7]
	global_load_ushort v157, v[162:163], off offset:192
	s_mov_b32 s6, 0x7006340
	v_lshl_add_u64 v[162:163], v[146:147], 0, s[6:7]
	global_load_ushort v159, v[162:163], off offset:192
	s_mov_b32 s6, 0x7007540
	v_lshl_add_u64 v[162:163], v[146:147], 0, s[6:7]
	global_load_ushort v151, v[162:163], off offset:192
	s_mov_b32 s6, 0x7008740
	v_lshl_add_u64 v[162:163], v[146:147], 0, s[6:7]
	global_load_ushort v189, v[162:163], off offset:192
	v_mov_b32_e32 v96, v137
	v_mov_b32_e32 v97, v137
	v_mov_b32_e32 v98, v137
	v_mov_b32_e32 v99, v137
	v_mov_b32_e32 v100, v137
	v_mov_b32_e32 v101, v137
	v_mov_b32_e32 v102, v137
	v_mov_b32_e32 v103, v137
	v_mov_b32_e32 v104, v137
	v_mov_b32_e32 v105, v137
	v_mov_b32_e32 v106, v137
	v_mov_b32_e32 v107, v137
	v_mov_b32_e32 v108, v137
	v_mov_b32_e32 v109, v137
	v_mov_b32_e32 v110, v137
	v_mov_b32_e32 v111, v137
	v_mov_b32_e32 v112, v137
	v_mov_b32_e32 v113, v137
	v_mov_b32_e32 v114, v137
	v_mov_b32_e32 v115, v137
	v_mov_b32_e32 v116, v137
	v_mov_b32_e32 v117, v137
	v_mov_b32_e32 v118, v137
	v_mov_b32_e32 v119, v137
	v_mov_b32_e32 v120, v137
	v_mov_b32_e32 v121, v137
	v_mov_b32_e32 v122, v137
	v_mov_b32_e32 v123, v137
	v_mov_b32_e32 v124, v137
	v_mov_b32_e32 v125, v137
	v_mov_b32_e32 v126, v137
	v_mov_b32_e32 v127, v137
	v_mov_b32_e32 v64, v137
	v_mov_b32_e32 v65, v137
	v_mov_b32_e32 v66, v137
	v_mov_b32_e32 v67, v137
	v_mov_b32_e32 v68, v137
	v_mov_b32_e32 v69, v137
	v_mov_b32_e32 v70, v137
	v_mov_b32_e32 v71, v137
	v_mov_b32_e32 v72, v137
	v_mov_b32_e32 v73, v137
	v_mov_b32_e32 v74, v137
	v_mov_b32_e32 v75, v137
	v_mov_b32_e32 v76, v137
	v_mov_b32_e32 v77, v137
	v_mov_b32_e32 v78, v137
	v_mov_b32_e32 v79, v137
	v_mov_b32_e32 v80, v137
	v_mov_b32_e32 v81, v137
	v_mov_b32_e32 v82, v137
	v_mov_b32_e32 v83, v137
	v_mov_b32_e32 v84, v137
	v_mov_b32_e32 v85, v137
	v_mov_b32_e32 v86, v137
	v_mov_b32_e32 v87, v137
	v_mov_b32_e32 v88, v137
	v_mov_b32_e32 v89, v137
	v_mov_b32_e32 v90, v137
	v_mov_b32_e32 v91, v137
	v_mov_b32_e32 v92, v137
	v_mov_b32_e32 v93, v137
	v_mov_b32_e32 v94, v137
	v_mov_b32_e32 v95, v137
	v_mov_b32_e32 v32, v137
	v_mov_b32_e32 v33, v137
	v_mov_b32_e32 v34, v137
	s_waitcnt vmcnt(48)
	v_max_f32_e32 v4, v3, v3
	v_min_f32_e32 v6, 0, v4
	v_mul_f32_e64 v4, |v3|, s27
	v_fma_f32 v5, |v3|, s27, -v4
	v_rndne_f32_e32 v7, v4
	v_fma_f32 v5, |v3|, s0, v5
	v_sub_f32_e32 v4, v4, v7
	v_add_f32_e32 v4, v4, v5
	v_exp_f32_e32 v4, v4
	v_cvt_i32_f32_e32 v5, v7
	s_mov_b32 s0, 0x42ce8ed0
	v_cmp_ngt_f32_e64 vcc, |v3|, s0
	s_mov_b32 s0, 0xc2b17218
	v_ldexp_f32 v4, v4, v5
	v_cndmask_b32_e32 v4, 0, v4, vcc
	v_cmp_nlt_f32_e64 vcc, |v3|, s0
	s_mov_b32 s0, 0x3f2aaaab
	v_mov_b32_e32 v35, v137
	v_cndmask_b32_e32 v3, v164, v4, vcc
	v_add_f32_e32 v7, 1.0, v3
	v_add_f32_e32 v4, -1.0, v7
	v_sub_f32_e32 v5, v4, v7
	v_add_f32_e32 v5, 1.0, v5
	v_sub_f32_e32 v4, v3, v4
	v_add_f32_e32 v8, v4, v5
	v_frexp_mant_f32_e32 v4, v7
	v_cmp_gt_f32_e32 vcc, s0, v4
	v_cvt_f64_f32_e32 v[4:5], v7
	v_frexp_exp_i32_f64_e32 v4, v[4:5]
	v_subbrev_co_u32_e32 v4, vcc, 0, v4, vcc
	v_sub_u32_e32 v5, 0, v4
	v_ldexp_f32 v7, v7, v5
	v_ldexp_f32 v5, v8, v5
	v_add_f32_e32 v8, -1.0, v7
	v_add_f32_e32 v9, 1.0, v8
	v_sub_f32_e32 v9, v7, v9
	v_add_f32_e32 v9, v5, v9
	v_add_f32_e32 v10, v8, v9
	v_sub_f32_e32 v8, v8, v10
	v_add_f32_e32 v8, v9, v8
	v_add_f32_e32 v9, 1.0, v7
	v_add_f32_e32 v11, -1.0, v9
	v_sub_f32_e32 v7, v7, v11
	v_add_f32_e32 v5, v5, v7
	v_add_f32_e32 v7, v9, v5
	v_sub_f32_e32 v9, v9, v7
	v_add_f32_e32 v5, v5, v9
	v_rcp_f32_e32 v9, v7
	v_cvt_f32_i32_e32 v4, v4
	s_mov_b32 s0, 0x3f317218
	v_mov_b32_e32 v36, v137
	v_mul_f32_e32 v11, v10, v9
	v_mul_f32_e32 v12, v7, v11
	v_fma_f32 v13, v11, v7, -v12
	v_fmac_f32_e32 v13, v11, v5
	v_add_f32_e32 v14, v12, v13
	v_sub_f32_e32 v15, v10, v14
	v_sub_f32_e32 v10, v10, v15
	v_sub_f32_e32 v12, v14, v12
	v_sub_f32_e32 v10, v10, v14
	v_add_f32_e32 v8, v8, v10
	v_sub_f32_e32 v10, v12, v13
	v_add_f32_e32 v8, v10, v8
	v_add_f32_e32 v10, v15, v8
	v_mul_f32_e32 v12, v9, v10
	v_mul_f32_e32 v13, v7, v12
	v_fma_f32 v7, v12, v7, -v13
	v_fmac_f32_e32 v7, v12, v5
	v_sub_f32_e32 v5, v15, v10
	v_add_f32_e32 v5, v8, v5
	v_add_f32_e32 v8, v13, v7
	v_sub_f32_e32 v14, v10, v8
	v_sub_f32_e32 v10, v10, v14
	v_sub_f32_e32 v13, v8, v13
	v_sub_f32_e32 v8, v10, v8
	v_add_f32_e32 v5, v5, v8
	v_sub_f32_e32 v7, v13, v7
	v_add_f32_e32 v5, v7, v5
	v_add_f32_e32 v7, v11, v12
	v_add_f32_e32 v5, v14, v5
	v_sub_f32_e32 v8, v7, v11
	v_mul_f32_e32 v5, v9, v5
	v_sub_f32_e32 v8, v12, v8
	v_add_f32_e32 v5, v8, v5
	v_mul_f32_e32 v11, 0x3f317218, v4
	v_add_f32_e32 v8, v7, v5
	v_fma_f32 v12, v4, s0, -v11
	v_mul_f32_e32 v9, v8, v8
	v_fmac_f32_e32 v12, 0xb102e308, v4
	v_sub_f32_e32 v4, v8, v7
	v_fmamk_f32 v10, v9, 0x3e9b6dac, v165
	v_sub_f32_e32 v4, v5, v4
	v_add_f32_e32 v5, v11, v12
	v_fmaak_f32 v10, v9, v10, 0x3f2aaada
	v_sub_f32_e32 v7, v5, v11
	v_ldexp_f32 v11, v8, 1
	v_mul_f32_e32 v8, v8, v9
	v_mul_f32_e32 v8, v8, v10
	v_add_f32_e32 v9, v11, v8
	v_sub_f32_e32 v10, v9, v11
	v_ldexp_f32 v4, v4, 1
	v_sub_f32_e32 v8, v8, v10
	v_add_f32_e32 v4, v4, v8
	v_add_f32_e32 v8, v9, v4
	v_sub_f32_e32 v9, v8, v9
	v_sub_f32_e32 v4, v4, v9
	v_add_f32_e32 v9, v5, v8
	v_sub_f32_e32 v10, v9, v5
	v_sub_f32_e32 v11, v9, v10
	v_sub_f32_e32 v7, v12, v7
	v_sub_f32_e32 v5, v5, v11
	v_sub_f32_e32 v8, v8, v10
	v_add_f32_e32 v5, v8, v5
	v_add_f32_e32 v8, v7, v4
	v_sub_f32_e32 v10, v8, v7
	v_sub_f32_e32 v11, v8, v10
	v_sub_f32_e32 v7, v7, v11
	v_sub_f32_e32 v4, v4, v10
	v_add_f32_e32 v5, v8, v5
	v_add_f32_e32 v4, v4, v7
	v_add_f32_e32 v7, v9, v5
	v_sub_f32_e32 v8, v7, v9
	v_sub_f32_e32 v5, v5, v8
	v_add_f32_e32 v4, v4, v5
	s_mov_b32 s0, 0x7f800000
	v_add_f32_e32 v4, v7, v4
	v_cmp_neq_f32_e32 vcc, s0, v3
	s_mov_b32 s0, 0x33800000
	v_mov_b32_e32 v37, v137
	v_cndmask_b32_e32 v4, v164, v4, vcc
	v_cmp_lt_f32_e64 vcc, |v3|, s0
	v_cmp_lt_i32_e64 s[0:1], v169, v167
	v_mov_b32_e32 v38, v137
	v_cndmask_b32_e32 v3, v4, v3, vcc
	v_cmp_lt_i32_e32 vcc, v168, v167
	v_sub_f32_e32 v3, v6, v3
	v_mov_b32_e32 v39, v137
	v_cndmask_b32_e32 v4, v168, v166, vcc
	v_lshlrev_b32_e32 v4, 2, v4
	ds_bpermute_b32 v4, v4, v3
	v_cmp_eq_u32_e32 vcc, 0, v1
	v_mov_b32_e32 v40, v137
	v_mov_b32_e32 v41, v137
	v_mov_b32_e32 v42, v137
	s_waitcnt lgkmcnt(0)
	v_add_f32_e32 v4, v3, v4
	v_cndmask_b32_e32 v3, v4, v3, vcc
	v_cndmask_b32_e64 v4, v169, v166, s[0:1]
	v_lshlrev_b32_e32 v4, 2, v4
	ds_bpermute_b32 v4, v4, v3
	v_cmp_gt_u32_e64 s[0:1], 2, v1
	v_mov_b32_e32 v43, v137
	v_mov_b32_e32 v44, v137
	v_mov_b32_e32 v45, v137
	s_waitcnt lgkmcnt(0)
	v_add_f32_e32 v4, v3, v4
	v_cndmask_b32_e64 v3, v4, v3, s[0:1]
	v_cmp_lt_i32_e64 s[0:1], v170, v167
	v_mov_b32_e32 v46, v137
	v_mov_b32_e32 v47, v137
	v_cndmask_b32_e64 v4, v170, v166, s[0:1]
	v_lshlrev_b32_e32 v4, 2, v4
	ds_bpermute_b32 v4, v4, v3
	v_cmp_gt_u32_e64 s[0:1], 4, v1
	v_mov_b32_e32 v48, v137
	v_mov_b32_e32 v49, v137
	v_mov_b32_e32 v50, v137
	s_waitcnt lgkmcnt(0)
	v_add_f32_e32 v4, v3, v4
	v_cndmask_b32_e64 v3, v4, v3, s[0:1]
	v_cmp_lt_i32_e64 s[0:1], v171, v167
	v_mov_b32_e32 v51, v137
	v_mov_b32_e32 v52, v137
	v_cndmask_b32_e64 v4, v171, v166, s[0:1]
	v_lshlrev_b32_e32 v4, 2, v4
	ds_bpermute_b32 v4, v4, v3
	v_cmp_gt_u32_e64 s[0:1], 8, v1
	v_mov_b32_e32 v53, v137
	v_mov_b32_e32 v54, v137
	v_mov_b32_e32 v55, v137
	s_waitcnt lgkmcnt(0)
	v_add_f32_e32 v4, v3, v4
	v_cndmask_b32_e64 v3, v4, v3, s[0:1]
	v_cmp_lt_i32_e64 s[0:1], v172, v167
	v_mov_b32_e32 v56, v137
	v_mov_b32_e32 v57, v137
	v_cndmask_b32_e64 v4, v172, v166, s[0:1]
	v_lshlrev_b32_e32 v4, 2, v4
	ds_bpermute_b32 v4, v4, v3
	v_cmp_gt_u32_e64 s[0:1], 16, v1
	v_mov_b32_e32 v58, v137
	v_mov_b32_e32 v59, v137
	v_mov_b32_e32 v60, v137
	s_waitcnt lgkmcnt(0)
	v_add_f32_e32 v4, v3, v4
	v_cndmask_b32_e64 v3, v4, v3, s[0:1]
	v_cmp_lt_i32_e64 s[0:1], v173, v167
	v_mov_b32_e32 v61, v137
	v_mov_b32_e32 v62, v137
	v_cndmask_b32_e64 v4, v173, v166, s[0:1]
	v_lshlrev_b32_e32 v4, 2, v4
	ds_bpermute_b32 v4, v4, v3
	v_cmp_gt_u32_e64 s[0:1], 32, v1
	v_mov_b32_e32 v63, v137
	v_mov_b32_e32 v5, v137
	v_mov_b32_e32 v6, v137
	s_waitcnt lgkmcnt(0)
	v_add_f32_e32 v1, v3, v4
	v_cndmask_b32_e64 v1, v1, v3, s[0:1]
	ds_bpermute_b32 v183, v175, v1
	v_cmp_lt_i32_e64 s[6:7], v177, v176
	v_mov_b32_e32 v4, v137
	v_mov_b32_e32 v7, v137
	v_mov_b32_e32 v8, v137
	v_mov_b32_e32 v9, v137
	s_waitcnt lgkmcnt(0)
	v_sub_f32_e32 v1, v183, v1
	v_add_f32_e32 v1, v2, v1
	v_cndmask_b32_e64 v2, v166, v177, s[6:7]
	v_lshlrev_b32_e32 v2, 2, v2
	ds_bpermute_b32 v2, v2, v1
	v_cmp_lt_i32_e64 s[6:7], v178, v176
	v_mov_b32_e32 v10, v137
	v_mov_b32_e32 v11, v137
	v_cndmask_b32_e64 v3, v166, v178, s[6:7]
	s_waitcnt lgkmcnt(0)
	v_max_f32_e32 v2, v2, v2
	v_max_f32_e32 v2, v1, v2
	v_lshlrev_b32_e32 v3, 2, v3
	ds_bpermute_b32 v3, v3, v2
	v_cmp_lt_i32_e64 s[6:7], v179, v176
	v_mov_b32_e32 v12, v137
	v_mov_b32_e32 v13, v137
	v_mov_b32_e32 v14, v137
	s_waitcnt lgkmcnt(0)
	v_max_f32_e32 v3, v3, v3
	v_max_f32_e32 v2, v2, v3
	v_cndmask_b32_e64 v3, v166, v179, s[6:7]
	v_lshlrev_b32_e32 v3, 2, v3
	ds_bpermute_b32 v3, v3, v2
	v_cmp_lt_i32_e64 s[6:7], v180, v176
	v_mov_b32_e32 v15, v137
	v_mov_b32_e32 v16, v137
	v_mov_b32_e32 v17, v137
	s_waitcnt lgkmcnt(0)
	v_max_f32_e32 v3, v3, v3
	v_max_f32_e32 v2, v2, v3
	v_cndmask_b32_e64 v3, v166, v180, s[6:7]
	v_lshlrev_b32_e32 v3, 2, v3
	ds_bpermute_b32 v3, v3, v2
	v_cmp_lt_i32_e64 s[6:7], v181, v176
	v_mov_b32_e32 v18, v137
	v_mov_b32_e32 v19, v137
	v_mov_b32_e32 v20, v137
	s_waitcnt lgkmcnt(0)
	v_max_f32_e32 v3, v3, v3
	v_max_f32_e32 v2, v2, v3
	v_cndmask_b32_e64 v3, v166, v181, s[6:7]
	v_lshlrev_b32_e32 v3, 2, v3
	ds_bpermute_b32 v3, v3, v2
	v_cmp_lt_i32_e64 s[6:7], v182, v176
	v_mov_b32_e32 v21, v137
	v_mov_b32_e32 v22, v137
	v_mov_b32_e32 v23, v137
	s_waitcnt lgkmcnt(0)
	v_max_f32_e32 v3, v3, v3
	v_max_f32_e32 v2, v2, v3
	v_cndmask_b32_e64 v3, v166, v182, s[6:7]
	v_lshlrev_b32_e32 v185, 2, v3
	ds_bpermute_b32 v3, v185, v2
	s_waitcnt lgkmcnt(0)
	v_max_f32_e32 v3, v3, v3
	v_max_f32_e32 v184, v2, v3
	v_sub_f32_e32 v1, v1, v184
	v_mul_f32_e32 v1, 0x3fb8aa3b, v1
	v_exp_f32_e32 v187, v1
	v_mov_b32_e32 v1, v137
	v_mov_b32_e32 v0, v137
	v_mov_b32_e32 v1, v137
	v_mov_b32_e32 v2, v137
	v_mov_b32_e32 v3, v137
	v_mov_b32_e32 v24, v137
	v_mov_b32_e32 v25, v137
	v_mov_b32_e32 v26, v137
	v_mov_b32_e32 v27, v137
	v_mov_b32_e32 v28, v137
	v_mov_b32_e32 v29, v137
	v_mov_b32_e32 v30, v137
	v_mov_b32_e32 v31, v137
	v_mov_b32_e32 v144, v137
	v_mov_b32_e32 v145, v137
	s_mov_b32 s7, 0
	ds_bpermute_b32 v150, v188, v187
	ds_bpermute_b32 v152, v188, v187 offset:4
	ds_bpermute_b32 v154, v188, v187 offset:8
	ds_bpermute_b32 v156, v188, v187 offset:12
	ds_bpermute_b32 v158, v188, v187 offset:16
	ds_bpermute_b32 v160, v188, v187 offset:20
	ds_bpermute_b32 v210, v188, v187 offset:24
	ds_bpermute_b32 v212, v188, v187 offset:28
	s_waitcnt vmcnt(32)
	v_lshlrev_b32_e32 v190, 16, v190
	v_lshlrev_b32_e32 v191, 16, v191
	v_lshlrev_b32_e32 v192, 16, v192
	v_lshlrev_b32_e32 v193, 16, v193
	v_lshlrev_b32_e32 v194, 16, v194
	v_lshlrev_b32_e32 v195, 16, v195
	v_lshlrev_b32_e32 v196, 16, v196
	v_lshlrev_b32_e32 v197, 16, v197
	v_lshlrev_b32_e32 v198, 16, v198
	v_lshlrev_b32_e32 v199, 16, v199
	v_lshlrev_b32_e32 v200, 16, v200
	v_lshlrev_b32_e32 v201, 16, v201
	v_lshlrev_b32_e32 v202, 16, v202
	v_lshlrev_b32_e32 v203, 16, v203
	v_lshlrev_b32_e32 v204, 16, v204
	v_lshlrev_b32_e32 v205, 16, v205
	s_waitcnt lgkmcnt(0)
	v_pk_fma_f32 v[144:145], v[150:151], v[190:191], v[144:145] op_sel_hi:[0,1,1]
	v_pk_mul_f32 v[190:191], v[150:151], v[190:191] op_sel_hi:[0,1]
	v_pk_fma_f32 v[144:145], v[152:153], v[192:193], v[144:145] op_sel_hi:[0,1,1]
	v_pk_mul_f32 v[192:193], v[152:153], v[192:193] op_sel_hi:[0,1]
	v_pk_fma_f32 v[144:145], v[154:155], v[194:195], v[144:145] op_sel_hi:[0,1,1]
	v_pk_mul_f32 v[194:195], v[154:155], v[194:195] op_sel_hi:[0,1]
	v_pk_fma_f32 v[144:145], v[156:157], v[196:197], v[144:145] op_sel_hi:[0,1,1]
	v_pk_mul_f32 v[196:197], v[156:157], v[196:197] op_sel_hi:[0,1]
	v_pk_fma_f32 v[144:145], v[158:159], v[198:199], v[144:145] op_sel_hi:[0,1,1]
	v_pk_mul_f32 v[198:199], v[158:159], v[198:199] op_sel_hi:[0,1]
	v_pk_fma_f32 v[144:145], v[160:161], v[200:201], v[144:145] op_sel_hi:[0,1,1]
	v_pk_mul_f32 v[200:201], v[160:161], v[200:201] op_sel_hi:[0,1]
	v_pk_fma_f32 v[144:145], v[210:211], v[202:203], v[144:145] op_sel_hi:[0,1,1]
	v_pk_mul_f32 v[202:203], v[210:211], v[202:203] op_sel_hi:[0,1]
	v_pk_fma_f32 v[144:145], v[212:213], v[204:205], v[144:145] op_sel_hi:[0,1,1]
	v_pk_mul_f32 v[204:205], v[212:213], v[204:205] op_sel_hi:[0,1]
	v_cvt_pk_bf16_f32 v128, v190, v192
	v_cvt_pk_bf16_f32 v132, v191, v193
	v_cvt_pk_bf16_f32 v129, v194, v196
	v_cvt_pk_bf16_f32 v133, v195, v197
	v_cvt_pk_bf16_f32 v130, v198, v200
	v_cvt_pk_bf16_f32 v134, v199, v201
	v_cvt_pk_bf16_f32 v131, v202, v204
	v_cvt_pk_bf16_f32 v135, v203, v205
	global_load_ushort v190, v[148:149], off offset:0
	global_load_ushort v192, v[148:149], off offset:128
	global_load_ushort v194, v[148:149], off offset:256
	global_load_ushort v196, v[148:149], off offset:384
	global_load_ushort v198, v[148:149], off offset:512
	global_load_ushort v200, v[148:149], off offset:640
	global_load_ushort v202, v[148:149], off offset:768
	global_load_ushort v204, v[148:149], off offset:896
	global_load_ushort v191, v[148:149], off offset:64
	global_load_ushort v193, v[148:149], off offset:192
	global_load_ushort v195, v[148:149], off offset:320
	global_load_ushort v197, v[148:149], off offset:448
	global_load_ushort v199, v[148:149], off offset:576
	global_load_ushort v201, v[148:149], off offset:704
	global_load_ushort v203, v[148:149], off offset:832
	global_load_ushort v205, v[148:149], off offset:960
	s_waitcnt vmcnt(40)
	v_perm_b32 v216, v217, v216, s28
	v_perm_b32 v217, v219, v218, s28
	v_perm_b32 v218, v221, v220, s28
	v_perm_b32 v219, v223, v222, s28
	s_nop 1
	v_mfma_f32_32x32x16_bf16 v[96:111], v[216:219], v[128:131], v[96:111]
	v_mfma_f32_32x32x16_bf16 v[112:127], v[216:219], v[132:135], v[112:127]
	s_mov_b32 s6, 0x7012940
	v_lshl_add_u64 v[162:163], v[146:147], 0, s[6:7]
	global_load_ushort v216, v[162:163], off offset:0
	s_mov_b32 s6, 0x7013b40
	v_lshl_add_u64 v[162:163], v[146:147], 0, s[6:7]
	global_load_ushort v217, v[162:163], off offset:0
	s_mov_b32 s6, 0x7014d40
	v_lshl_add_u64 v[162:163], v[146:147], 0, s[6:7]
	global_load_ushort v218, v[162:163], off offset:0
	s_mov_b32 s6, 0x7015f40
	v_lshl_add_u64 v[162:163], v[146:147], 0, s[6:7]
	global_load_ushort v219, v[162:163], off offset:0
	s_mov_b32 s6, 0x7017140
	v_lshl_add_u64 v[162:163], v[146:147], 0, s[6:7]
	global_load_ushort v220, v[162:163], off offset:0
	s_mov_b32 s6, 0x7018340
	v_lshl_add_u64 v[162:163], v[146:147], 0, s[6:7]
	global_load_ushort v221, v[162:163], off offset:0
	s_mov_b32 s6, 0x7019540
	v_lshl_add_u64 v[162:163], v[146:147], 0, s[6:7]
	global_load_ushort v222, v[162:163], off offset:0
	s_mov_b32 s6, 0x701a740
	v_lshl_add_u64 v[162:163], v[146:147], 0, s[6:7]
	global_load_ushort v223, v[162:163], off offset:0
	s_waitcnt vmcnt(40)
	v_perm_b32 v224, v225, v224, s28
	v_perm_b32 v225, v227, v226, s28
	v_perm_b32 v226, v245, v244, s28
	v_perm_b32 v227, v247, v246, s28
	s_nop 1
	v_mfma_f32_32x32x16_bf16 v[64:79], v[224:227], v[128:131], v[64:79]
	v_mfma_f32_32x32x16_bf16 v[80:95], v[224:227], v[132:135], v[80:95]
	s_mov_b32 s6, 0x7012940
	v_lshl_add_u64 v[162:163], v[146:147], 0, s[6:7]
	global_load_ushort v224, v[162:163], off offset:64
	s_mov_b32 s6, 0x7013b40
	v_lshl_add_u64 v[162:163], v[146:147], 0, s[6:7]
	global_load_ushort v225, v[162:163], off offset:64
	s_mov_b32 s6, 0x7014d40
	v_lshl_add_u64 v[162:163], v[146:147], 0, s[6:7]
	global_load_ushort v226, v[162:163], off offset:64
	s_mov_b32 s6, 0x7015f40
	v_lshl_add_u64 v[162:163], v[146:147], 0, s[6:7]
	global_load_ushort v227, v[162:163], off offset:64
	s_mov_b32 s6, 0x7017140
	v_lshl_add_u64 v[162:163], v[146:147], 0, s[6:7]
	global_load_ushort v244, v[162:163], off offset:64
	s_mov_b32 s6, 0x7018340
	v_lshl_add_u64 v[162:163], v[146:147], 0, s[6:7]
	global_load_ushort v245, v[162:163], off offset:64
	s_mov_b32 s6, 0x7019540
	v_lshl_add_u64 v[162:163], v[146:147], 0, s[6:7]
	global_load_ushort v246, v[162:163], off offset:64
	s_mov_b32 s6, 0x701a740
	v_lshl_add_u64 v[162:163], v[146:147], 0, s[6:7]
	global_load_ushort v247, v[162:163], off offset:64
	s_waitcnt vmcnt(40)
	v_perm_b32 v248, v249, v248, s28
	v_perm_b32 v249, v251, v250, s28
	v_perm_b32 v250, v253, v252, s28
	v_perm_b32 v251, v155, v153, s28
	s_nop 1
	v_mfma_f32_32x32x16_bf16 v[32:47], v[248:251], v[128:131], v[32:47]
	v_mfma_f32_32x32x16_bf16 v[48:63], v[248:251], v[132:135], v[48:63]
	s_mov_b32 s6, 0x7012940
	v_lshl_add_u64 v[162:163], v[146:147], 0, s[6:7]
	global_load_ushort v248, v[162:163], off offset:128
	s_mov_b32 s6, 0x7013b40
	v_lshl_add_u64 v[162:163], v[146:147], 0, s[6:7]
	global_load_ushort v249, v[162:163], off offset:128
	s_mov_b32 s6, 0x7014d40
	v_lshl_add_u64 v[162:163], v[146:147], 0, s[6:7]
	global_load_ushort v250, v[162:163], off offset:128
	s_mov_b32 s6, 0x7015f40
	v_lshl_add_u64 v[162:163], v[146:147], 0, s[6:7]
	global_load_ushort v251, v[162:163], off offset:128
	s_mov_b32 s6, 0x7017140
	v_lshl_add_u64 v[162:163], v[146:147], 0, s[6:7]
	global_load_ushort v252, v[162:163], off offset:128
	s_mov_b32 s6, 0x7018340
	v_lshl_add_u64 v[162:163], v[146:147], 0, s[6:7]
	global_load_ushort v253, v[162:163], off offset:128
	s_mov_b32 s6, 0x7019540
	v_lshl_add_u64 v[162:163], v[146:147], 0, s[6:7]
	global_load_ushort v153, v[162:163], off offset:128
	s_mov_b32 s6, 0x701a740
	v_lshl_add_u64 v[162:163], v[146:147], 0, s[6:7]
	global_load_ushort v155, v[162:163], off offset:128
	s_waitcnt vmcnt(40)
	v_perm_b32 v206, v207, v206, s28
	v_perm_b32 v207, v209, v208, s28
	v_perm_b32 v208, v159, v157, s28
	v_perm_b32 v209, v189, v151, s28
	s_nop 1
	v_mfma_f32_32x32x16_bf16 v[0:15], v[206:209], v[128:131], v[0:15]
	v_mfma_f32_32x32x16_bf16 v[16:31], v[206:209], v[132:135], v[16:31]
	s_mov_b32 s6, 0x7012940
	v_lshl_add_u64 v[162:163], v[146:147], 0, s[6:7]
	global_load_ushort v206, v[162:163], off offset:192
	s_mov_b32 s6, 0x7013b40
	v_lshl_add_u64 v[162:163], v[146:147], 0, s[6:7]
	global_load_ushort v207, v[162:163], off offset:192
	s_mov_b32 s6, 0x7014d40
	v_lshl_add_u64 v[162:163], v[146:147], 0, s[6:7]
	global_load_ushort v208, v[162:163], off offset:192
	s_mov_b32 s6, 0x7015f40
	v_lshl_add_u64 v[162:163], v[146:147], 0, s[6:7]
	global_load_ushort v209, v[162:163], off offset:192
	s_mov_b32 s6, 0x7017140
	v_lshl_add_u64 v[162:163], v[146:147], 0, s[6:7]
	global_load_ushort v157, v[162:163], off offset:192
	s_mov_b32 s6, 0x7018340
	v_lshl_add_u64 v[162:163], v[146:147], 0, s[6:7]
	global_load_ushort v159, v[162:163], off offset:192
	s_mov_b32 s6, 0x7019540
	v_lshl_add_u64 v[162:163], v[146:147], 0, s[6:7]
	global_load_ushort v151, v[162:163], off offset:192
	s_mov_b32 s6, 0x701a740
	v_lshl_add_u64 v[162:163], v[146:147], 0, s[6:7]
	global_load_ushort v189, v[162:163], off offset:192
	ds_bpermute_b32 v150, v188, v187 offset:64
	ds_bpermute_b32 v152, v188, v187 offset:68
	ds_bpermute_b32 v154, v188, v187 offset:72
	ds_bpermute_b32 v156, v188, v187 offset:76
	ds_bpermute_b32 v158, v188, v187 offset:80
	ds_bpermute_b32 v160, v188, v187 offset:84
	ds_bpermute_b32 v210, v188, v187 offset:88
	ds_bpermute_b32 v212, v188, v187 offset:92
	s_waitcnt vmcnt(32)
	v_lshlrev_b32_e32 v190, 16, v190
	v_lshlrev_b32_e32 v191, 16, v191
	v_lshlrev_b32_e32 v192, 16, v192
	v_lshlrev_b32_e32 v193, 16, v193
	v_lshlrev_b32_e32 v194, 16, v194
	v_lshlrev_b32_e32 v195, 16, v195
	v_lshlrev_b32_e32 v196, 16, v196
	v_lshlrev_b32_e32 v197, 16, v197
	v_lshlrev_b32_e32 v198, 16, v198
	v_lshlrev_b32_e32 v199, 16, v199
	v_lshlrev_b32_e32 v200, 16, v200
	v_lshlrev_b32_e32 v201, 16, v201
	v_lshlrev_b32_e32 v202, 16, v202
	v_lshlrev_b32_e32 v203, 16, v203
	v_lshlrev_b32_e32 v204, 16, v204
	v_lshlrev_b32_e32 v205, 16, v205
	s_waitcnt lgkmcnt(0)
	v_pk_fma_f32 v[144:145], v[150:151], v[190:191], v[144:145] op_sel_hi:[0,1,1]
	v_pk_mul_f32 v[190:191], v[150:151], v[190:191] op_sel_hi:[0,1]
	v_pk_fma_f32 v[144:145], v[152:153], v[192:193], v[144:145] op_sel_hi:[0,1,1]
	v_pk_mul_f32 v[192:193], v[152:153], v[192:193] op_sel_hi:[0,1]
	v_pk_fma_f32 v[144:145], v[154:155], v[194:195], v[144:145] op_sel_hi:[0,1,1]
	v_pk_mul_f32 v[194:195], v[154:155], v[194:195] op_sel_hi:[0,1]
	v_pk_fma_f32 v[144:145], v[156:157], v[196:197], v[144:145] op_sel_hi:[0,1,1]
	v_pk_mul_f32 v[196:197], v[156:157], v[196:197] op_sel_hi:[0,1]
	v_pk_fma_f32 v[144:145], v[158:159], v[198:199], v[144:145] op_sel_hi:[0,1,1]
	v_pk_mul_f32 v[198:199], v[158:159], v[198:199] op_sel_hi:[0,1]
	v_pk_fma_f32 v[144:145], v[160:161], v[200:201], v[144:145] op_sel_hi:[0,1,1]
	v_pk_mul_f32 v[200:201], v[160:161], v[200:201] op_sel_hi:[0,1]
	v_pk_fma_f32 v[144:145], v[210:211], v[202:203], v[144:145] op_sel_hi:[0,1,1]
	v_pk_mul_f32 v[202:203], v[210:211], v[202:203] op_sel_hi:[0,1]
	v_pk_fma_f32 v[144:145], v[212:213], v[204:205], v[144:145] op_sel_hi:[0,1,1]
	v_pk_mul_f32 v[204:205], v[212:213], v[204:205] op_sel_hi:[0,1]
	v_cvt_pk_bf16_f32 v128, v190, v192
	v_cvt_pk_bf16_f32 v132, v191, v193
	v_cvt_pk_bf16_f32 v129, v194, v196
	v_cvt_pk_bf16_f32 v133, v195, v197
	v_cvt_pk_bf16_f32 v130, v198, v200
	v_cvt_pk_bf16_f32 v134, v199, v201
	v_cvt_pk_bf16_f32 v131, v202, v204
	v_cvt_pk_bf16_f32 v135, v203, v205
	s_mov_b32 s6, 0x1000
	v_lshl_add_u64 v[148:149], v[148:149], 0, s[6:7]
	global_load_ushort v190, v[148:149], off offset:-2048
	global_load_ushort v192, v[148:149], off offset:-1920
	global_load_ushort v194, v[148:149], off offset:-1792
	global_load_ushort v196, v[148:149], off offset:-1664
	global_load_ushort v198, v[148:149], off offset:-1536
	global_load_ushort v200, v[148:149], off offset:-1408
	global_load_ushort v202, v[148:149], off offset:-1280
	global_load_ushort v204, v[148:149], off offset:-1152
	global_load_ushort v191, v[148:149], off offset:-1984
	global_load_ushort v193, v[148:149], off offset:-1856
	global_load_ushort v195, v[148:149], off offset:-1728
	global_load_ushort v197, v[148:149], off offset:-1600
	global_load_ushort v199, v[148:149], off offset:-1472
	global_load_ushort v201, v[148:149], off offset:-1344
	global_load_ushort v203, v[148:149], off offset:-1216
	global_load_ushort v205, v[148:149], off offset:-1088
	s_waitcnt vmcnt(40)
	v_perm_b32 v216, v217, v216, s28
	v_perm_b32 v217, v219, v218, s28
	v_perm_b32 v218, v221, v220, s28
	v_perm_b32 v219, v223, v222, s28
	s_nop 1
	v_mfma_f32_32x32x16_bf16 v[96:111], v[216:219], v[128:131], v[96:111]
	v_mfma_f32_32x32x16_bf16 v[112:127], v[216:219], v[132:135], v[112:127]
	s_mov_b32 s6, 0x7024940
	v_lshl_add_u64 v[162:163], v[146:147], 0, s[6:7]
	global_load_ushort v216, v[162:163], off offset:0
	s_mov_b32 s6, 0x7025b40
	v_lshl_add_u64 v[162:163], v[146:147], 0, s[6:7]
	global_load_ushort v217, v[162:163], off offset:0
	s_mov_b32 s6, 0x7026d40
	v_lshl_add_u64 v[162:163], v[146:147], 0, s[6:7]
	global_load_ushort v218, v[162:163], off offset:0
	s_mov_b32 s6, 0x7027f40
	v_lshl_add_u64 v[162:163], v[146:147], 0, s[6:7]
	global_load_ushort v219, v[162:163], off offset:0
	s_mov_b32 s6, 0x7029140
	v_lshl_add_u64 v[162:163], v[146:147], 0, s[6:7]
	global_load_ushort v220, v[162:163], off offset:0
	s_mov_b32 s6, 0x702a340
	v_lshl_add_u64 v[162:163], v[146:147], 0, s[6:7]
	global_load_ushort v221, v[162:163], off offset:0
	s_mov_b32 s6, 0x702b540
	v_lshl_add_u64 v[162:163], v[146:147], 0, s[6:7]
	global_load_ushort v222, v[162:163], off offset:0
	s_mov_b32 s6, 0x702c740
	v_lshl_add_u64 v[162:163], v[146:147], 0, s[6:7]
	global_load_ushort v223, v[162:163], off offset:0
	s_waitcnt vmcnt(40)
	v_perm_b32 v224, v225, v224, s28
	v_perm_b32 v225, v227, v226, s28
	v_perm_b32 v226, v245, v244, s28
	v_perm_b32 v227, v247, v246, s28
	s_nop 1
	v_mfma_f32_32x32x16_bf16 v[64:79], v[224:227], v[128:131], v[64:79]
	v_mfma_f32_32x32x16_bf16 v[80:95], v[224:227], v[132:135], v[80:95]
	s_mov_b32 s6, 0x7024940
	v_lshl_add_u64 v[162:163], v[146:147], 0, s[6:7]
	global_load_ushort v224, v[162:163], off offset:64
	s_mov_b32 s6, 0x7025b40
	v_lshl_add_u64 v[162:163], v[146:147], 0, s[6:7]
	global_load_ushort v225, v[162:163], off offset:64
	s_mov_b32 s6, 0x7026d40
	v_lshl_add_u64 v[162:163], v[146:147], 0, s[6:7]
	global_load_ushort v226, v[162:163], off offset:64
	s_mov_b32 s6, 0x7027f40
	v_lshl_add_u64 v[162:163], v[146:147], 0, s[6:7]
	global_load_ushort v227, v[162:163], off offset:64
	s_mov_b32 s6, 0x7029140
	v_lshl_add_u64 v[162:163], v[146:147], 0, s[6:7]
	global_load_ushort v244, v[162:163], off offset:64
	s_mov_b32 s6, 0x702a340
	v_lshl_add_u64 v[162:163], v[146:147], 0, s[6:7]
	global_load_ushort v245, v[162:163], off offset:64
	s_mov_b32 s6, 0x702b540
	v_lshl_add_u64 v[162:163], v[146:147], 0, s[6:7]
	global_load_ushort v246, v[162:163], off offset:64
	s_mov_b32 s6, 0x702c740
	v_lshl_add_u64 v[162:163], v[146:147], 0, s[6:7]
	global_load_ushort v247, v[162:163], off offset:64
	s_waitcnt vmcnt(40)
	v_perm_b32 v248, v249, v248, s28
	v_perm_b32 v249, v251, v250, s28
	v_perm_b32 v250, v253, v252, s28
	v_perm_b32 v251, v155, v153, s28
	s_nop 1
	v_mfma_f32_32x32x16_bf16 v[32:47], v[248:251], v[128:131], v[32:47]
	v_mfma_f32_32x32x16_bf16 v[48:63], v[248:251], v[132:135], v[48:63]
	s_mov_b32 s6, 0x7024940
	v_lshl_add_u64 v[162:163], v[146:147], 0, s[6:7]
	global_load_ushort v248, v[162:163], off offset:128
	s_mov_b32 s6, 0x7025b40
	v_lshl_add_u64 v[162:163], v[146:147], 0, s[6:7]
	global_load_ushort v249, v[162:163], off offset:128
	s_mov_b32 s6, 0x7026d40
	v_lshl_add_u64 v[162:163], v[146:147], 0, s[6:7]
	global_load_ushort v250, v[162:163], off offset:128
	s_mov_b32 s6, 0x7027f40
	v_lshl_add_u64 v[162:163], v[146:147], 0, s[6:7]
	global_load_ushort v251, v[162:163], off offset:128
	s_mov_b32 s6, 0x7029140
	v_lshl_add_u64 v[162:163], v[146:147], 0, s[6:7]
	global_load_ushort v252, v[162:163], off offset:128
	s_mov_b32 s6, 0x702a340
	v_lshl_add_u64 v[162:163], v[146:147], 0, s[6:7]
	global_load_ushort v253, v[162:163], off offset:128
	s_mov_b32 s6, 0x702b540
	v_lshl_add_u64 v[162:163], v[146:147], 0, s[6:7]
	global_load_ushort v153, v[162:163], off offset:128
	s_mov_b32 s6, 0x702c740
	v_lshl_add_u64 v[162:163], v[146:147], 0, s[6:7]
	global_load_ushort v155, v[162:163], off offset:128
	s_waitcnt vmcnt(40)
	v_perm_b32 v206, v207, v206, s28
	v_perm_b32 v207, v209, v208, s28
	v_perm_b32 v208, v159, v157, s28
	v_perm_b32 v209, v189, v151, s28
	s_nop 1
	v_mfma_f32_32x32x16_bf16 v[0:15], v[206:209], v[128:131], v[0:15]
	v_mfma_f32_32x32x16_bf16 v[16:31], v[206:209], v[132:135], v[16:31]
	s_mov_b32 s6, 0x7024940
	v_lshl_add_u64 v[162:163], v[146:147], 0, s[6:7]
	global_load_ushort v206, v[162:163], off offset:192
	s_mov_b32 s6, 0x7025b40
	v_lshl_add_u64 v[162:163], v[146:147], 0, s[6:7]
	global_load_ushort v207, v[162:163], off offset:192
	s_mov_b32 s6, 0x7026d40
	v_lshl_add_u64 v[162:163], v[146:147], 0, s[6:7]
	global_load_ushort v208, v[162:163], off offset:192
	s_mov_b32 s6, 0x7027f40
	v_lshl_add_u64 v[162:163], v[146:147], 0, s[6:7]
	global_load_ushort v209, v[162:163], off offset:192
	s_mov_b32 s6, 0x7029140
	v_lshl_add_u64 v[162:163], v[146:147], 0, s[6:7]
	global_load_ushort v157, v[162:163], off offset:192
	s_mov_b32 s6, 0x702a340
	v_lshl_add_u64 v[162:163], v[146:147], 0, s[6:7]
	global_load_ushort v159, v[162:163], off offset:192
	s_mov_b32 s6, 0x702b540
	v_lshl_add_u64 v[162:163], v[146:147], 0, s[6:7]
	global_load_ushort v151, v[162:163], off offset:192
	s_mov_b32 s6, 0x702c740
	v_lshl_add_u64 v[162:163], v[146:147], 0, s[6:7]
	global_load_ushort v189, v[162:163], off offset:192
	ds_bpermute_b32 v150, v188, v187 offset:128
	ds_bpermute_b32 v152, v188, v187 offset:132
	ds_bpermute_b32 v154, v188, v187 offset:136
	ds_bpermute_b32 v156, v188, v187 offset:140
	ds_bpermute_b32 v158, v188, v187 offset:144
	ds_bpermute_b32 v160, v188, v187 offset:148
	ds_bpermute_b32 v210, v188, v187 offset:152
	ds_bpermute_b32 v212, v188, v187 offset:156
	s_waitcnt vmcnt(32)
	v_lshlrev_b32_e32 v190, 16, v190
	v_lshlrev_b32_e32 v191, 16, v191
	v_lshlrev_b32_e32 v192, 16, v192
	v_lshlrev_b32_e32 v193, 16, v193
	v_lshlrev_b32_e32 v194, 16, v194
	v_lshlrev_b32_e32 v195, 16, v195
	v_lshlrev_b32_e32 v196, 16, v196
	v_lshlrev_b32_e32 v197, 16, v197
	v_lshlrev_b32_e32 v198, 16, v198
	v_lshlrev_b32_e32 v199, 16, v199
	v_lshlrev_b32_e32 v200, 16, v200
	v_lshlrev_b32_e32 v201, 16, v201
	v_lshlrev_b32_e32 v202, 16, v202
	v_lshlrev_b32_e32 v203, 16, v203
	v_lshlrev_b32_e32 v204, 16, v204
	v_lshlrev_b32_e32 v205, 16, v205
	s_waitcnt lgkmcnt(0)
	v_pk_fma_f32 v[144:145], v[150:151], v[190:191], v[144:145] op_sel_hi:[0,1,1]
	v_pk_mul_f32 v[190:191], v[150:151], v[190:191] op_sel_hi:[0,1]
	v_pk_fma_f32 v[144:145], v[152:153], v[192:193], v[144:145] op_sel_hi:[0,1,1]
	v_pk_mul_f32 v[192:193], v[152:153], v[192:193] op_sel_hi:[0,1]
	v_pk_fma_f32 v[144:145], v[154:155], v[194:195], v[144:145] op_sel_hi:[0,1,1]
	v_pk_mul_f32 v[194:195], v[154:155], v[194:195] op_sel_hi:[0,1]
	v_pk_fma_f32 v[144:145], v[156:157], v[196:197], v[144:145] op_sel_hi:[0,1,1]
	v_pk_mul_f32 v[196:197], v[156:157], v[196:197] op_sel_hi:[0,1]
	v_pk_fma_f32 v[144:145], v[158:159], v[198:199], v[144:145] op_sel_hi:[0,1,1]
	v_pk_mul_f32 v[198:199], v[158:159], v[198:199] op_sel_hi:[0,1]
	v_pk_fma_f32 v[144:145], v[160:161], v[200:201], v[144:145] op_sel_hi:[0,1,1]
	v_pk_mul_f32 v[200:201], v[160:161], v[200:201] op_sel_hi:[0,1]
	v_pk_fma_f32 v[144:145], v[210:211], v[202:203], v[144:145] op_sel_hi:[0,1,1]
	v_pk_mul_f32 v[202:203], v[210:211], v[202:203] op_sel_hi:[0,1]
	v_pk_fma_f32 v[144:145], v[212:213], v[204:205], v[144:145] op_sel_hi:[0,1,1]
	v_pk_mul_f32 v[204:205], v[212:213], v[204:205] op_sel_hi:[0,1]
	v_cvt_pk_bf16_f32 v128, v190, v192
	v_cvt_pk_bf16_f32 v132, v191, v193
	v_cvt_pk_bf16_f32 v129, v194, v196
	v_cvt_pk_bf16_f32 v133, v195, v197
	v_cvt_pk_bf16_f32 v130, v198, v200
	v_cvt_pk_bf16_f32 v134, v199, v201
	v_cvt_pk_bf16_f32 v131, v202, v204
	v_cvt_pk_bf16_f32 v135, v203, v205
	global_load_ushort v190, v[148:149], off offset:0
	global_load_ushort v192, v[148:149], off offset:128
	global_load_ushort v194, v[148:149], off offset:256
	global_load_ushort v196, v[148:149], off offset:384
	global_load_ushort v198, v[148:149], off offset:512
	global_load_ushort v200, v[148:149], off offset:640
	global_load_ushort v202, v[148:149], off offset:768
	global_load_ushort v204, v[148:149], off offset:896
	global_load_ushort v191, v[148:149], off offset:64
	global_load_ushort v193, v[148:149], off offset:192
	global_load_ushort v195, v[148:149], off offset:320
	global_load_ushort v197, v[148:149], off offset:448
	global_load_ushort v199, v[148:149], off offset:576
	global_load_ushort v201, v[148:149], off offset:704
	global_load_ushort v203, v[148:149], off offset:832
	global_load_ushort v205, v[148:149], off offset:960
	s_waitcnt vmcnt(40)
	v_perm_b32 v216, v217, v216, s28
	v_perm_b32 v217, v219, v218, s28
	v_perm_b32 v218, v221, v220, s28
	v_perm_b32 v219, v223, v222, s28
	s_nop 1
	v_mfma_f32_32x32x16_bf16 v[96:111], v[216:219], v[128:131], v[96:111]
	v_mfma_f32_32x32x16_bf16 v[112:127], v[216:219], v[132:135], v[112:127]
	s_mov_b32 s6, 0x7036940
	v_lshl_add_u64 v[162:163], v[146:147], 0, s[6:7]
	global_load_ushort v216, v[162:163], off offset:0
	s_mov_b32 s6, 0x7037b40
	v_lshl_add_u64 v[162:163], v[146:147], 0, s[6:7]
	global_load_ushort v217, v[162:163], off offset:0
	s_mov_b32 s6, 0x7038d40
	v_lshl_add_u64 v[162:163], v[146:147], 0, s[6:7]
	global_load_ushort v218, v[162:163], off offset:0
	s_mov_b32 s6, 0x7039f40
	v_lshl_add_u64 v[162:163], v[146:147], 0, s[6:7]
	global_load_ushort v219, v[162:163], off offset:0
	s_mov_b32 s6, 0x703b140
	v_lshl_add_u64 v[162:163], v[146:147], 0, s[6:7]
	global_load_ushort v220, v[162:163], off offset:0
	s_mov_b32 s6, 0x703c340
	v_lshl_add_u64 v[162:163], v[146:147], 0, s[6:7]
	global_load_ushort v221, v[162:163], off offset:0
	s_mov_b32 s6, 0x703d540
	v_lshl_add_u64 v[162:163], v[146:147], 0, s[6:7]
	global_load_ushort v222, v[162:163], off offset:0
	s_mov_b32 s6, 0x703e740
	v_lshl_add_u64 v[162:163], v[146:147], 0, s[6:7]
	global_load_ushort v223, v[162:163], off offset:0
	s_waitcnt vmcnt(40)
	v_perm_b32 v224, v225, v224, s28
	v_perm_b32 v225, v227, v226, s28
	v_perm_b32 v226, v245, v244, s28
	v_perm_b32 v227, v247, v246, s28
	s_nop 1
	v_mfma_f32_32x32x16_bf16 v[64:79], v[224:227], v[128:131], v[64:79]
	v_mfma_f32_32x32x16_bf16 v[80:95], v[224:227], v[132:135], v[80:95]
	s_mov_b32 s6, 0x7036940
	v_lshl_add_u64 v[162:163], v[146:147], 0, s[6:7]
	global_load_ushort v224, v[162:163], off offset:64
	s_mov_b32 s6, 0x7037b40
	v_lshl_add_u64 v[162:163], v[146:147], 0, s[6:7]
	global_load_ushort v225, v[162:163], off offset:64
	s_mov_b32 s6, 0x7038d40
	v_lshl_add_u64 v[162:163], v[146:147], 0, s[6:7]
	global_load_ushort v226, v[162:163], off offset:64
	s_mov_b32 s6, 0x7039f40
	v_lshl_add_u64 v[162:163], v[146:147], 0, s[6:7]
	global_load_ushort v227, v[162:163], off offset:64
	s_mov_b32 s6, 0x703b140
	v_lshl_add_u64 v[162:163], v[146:147], 0, s[6:7]
	global_load_ushort v244, v[162:163], off offset:64
	s_mov_b32 s6, 0x703c340
	v_lshl_add_u64 v[162:163], v[146:147], 0, s[6:7]
	global_load_ushort v245, v[162:163], off offset:64
	s_mov_b32 s6, 0x703d540
	v_lshl_add_u64 v[162:163], v[146:147], 0, s[6:7]
	global_load_ushort v246, v[162:163], off offset:64
	s_mov_b32 s6, 0x703e740
	v_lshl_add_u64 v[162:163], v[146:147], 0, s[6:7]
	global_load_ushort v247, v[162:163], off offset:64
	s_waitcnt vmcnt(40)
	v_perm_b32 v248, v249, v248, s28
	v_perm_b32 v249, v251, v250, s28
	v_perm_b32 v250, v253, v252, s28
	v_perm_b32 v251, v155, v153, s28
	s_nop 1
	v_mfma_f32_32x32x16_bf16 v[32:47], v[248:251], v[128:131], v[32:47]
	v_mfma_f32_32x32x16_bf16 v[48:63], v[248:251], v[132:135], v[48:63]
	s_mov_b32 s6, 0x7036940
	v_lshl_add_u64 v[162:163], v[146:147], 0, s[6:7]
	global_load_ushort v248, v[162:163], off offset:128
	s_mov_b32 s6, 0x7037b40
	v_lshl_add_u64 v[162:163], v[146:147], 0, s[6:7]
	global_load_ushort v249, v[162:163], off offset:128
	s_mov_b32 s6, 0x7038d40
	v_lshl_add_u64 v[162:163], v[146:147], 0, s[6:7]
	global_load_ushort v250, v[162:163], off offset:128
	s_mov_b32 s6, 0x7039f40
	v_lshl_add_u64 v[162:163], v[146:147], 0, s[6:7]
	global_load_ushort v251, v[162:163], off offset:128
	s_mov_b32 s6, 0x703b140
	v_lshl_add_u64 v[162:163], v[146:147], 0, s[6:7]
	global_load_ushort v252, v[162:163], off offset:128
	s_mov_b32 s6, 0x703c340
	v_lshl_add_u64 v[162:163], v[146:147], 0, s[6:7]
	global_load_ushort v253, v[162:163], off offset:128
	s_mov_b32 s6, 0x703d540
	v_lshl_add_u64 v[162:163], v[146:147], 0, s[6:7]
	global_load_ushort v153, v[162:163], off offset:128
	s_mov_b32 s6, 0x703e740
	v_lshl_add_u64 v[162:163], v[146:147], 0, s[6:7]
	global_load_ushort v155, v[162:163], off offset:128
	s_waitcnt vmcnt(40)
	v_perm_b32 v206, v207, v206, s28
	v_perm_b32 v207, v209, v208, s28
	v_perm_b32 v208, v159, v157, s28
	v_perm_b32 v209, v189, v151, s28
	s_nop 1
	v_mfma_f32_32x32x16_bf16 v[0:15], v[206:209], v[128:131], v[0:15]
	v_mfma_f32_32x32x16_bf16 v[16:31], v[206:209], v[132:135], v[16:31]
	s_mov_b32 s6, 0x7036940
	v_lshl_add_u64 v[162:163], v[146:147], 0, s[6:7]
	global_load_ushort v206, v[162:163], off offset:192
	s_mov_b32 s6, 0x7037b40
	v_lshl_add_u64 v[162:163], v[146:147], 0, s[6:7]
	global_load_ushort v207, v[162:163], off offset:192
	s_mov_b32 s6, 0x7038d40
	v_lshl_add_u64 v[162:163], v[146:147], 0, s[6:7]
	global_load_ushort v208, v[162:163], off offset:192
	s_mov_b32 s6, 0x7039f40
	v_lshl_add_u64 v[162:163], v[146:147], 0, s[6:7]
	global_load_ushort v209, v[162:163], off offset:192
	s_mov_b32 s6, 0x703b140
	v_lshl_add_u64 v[162:163], v[146:147], 0, s[6:7]
	global_load_ushort v157, v[162:163], off offset:192
	s_mov_b32 s6, 0x703c340
	v_lshl_add_u64 v[162:163], v[146:147], 0, s[6:7]
	global_load_ushort v159, v[162:163], off offset:192
	s_mov_b32 s6, 0x703d540
	v_lshl_add_u64 v[162:163], v[146:147], 0, s[6:7]
	global_load_ushort v151, v[162:163], off offset:192
	s_mov_b32 s6, 0x703e740
	v_lshl_add_u64 v[162:163], v[146:147], 0, s[6:7]
	global_load_ushort v189, v[162:163], off offset:192
	ds_bpermute_b32 v150, v188, v187 offset:192
	ds_bpermute_b32 v152, v188, v187 offset:196
	ds_bpermute_b32 v154, v188, v187 offset:200
	ds_bpermute_b32 v156, v188, v187 offset:204
	ds_bpermute_b32 v158, v188, v187 offset:208
	ds_bpermute_b32 v160, v188, v187 offset:212
	ds_bpermute_b32 v210, v188, v187 offset:216
	ds_bpermute_b32 v212, v188, v187 offset:220
	s_waitcnt vmcnt(32)
	v_lshlrev_b32_e32 v190, 16, v190
	v_lshlrev_b32_e32 v191, 16, v191
	v_lshlrev_b32_e32 v192, 16, v192
	v_lshlrev_b32_e32 v193, 16, v193
	v_lshlrev_b32_e32 v194, 16, v194
	v_lshlrev_b32_e32 v195, 16, v195
	v_lshlrev_b32_e32 v196, 16, v196
	v_lshlrev_b32_e32 v197, 16, v197
	v_lshlrev_b32_e32 v198, 16, v198
	v_lshlrev_b32_e32 v199, 16, v199
	v_lshlrev_b32_e32 v200, 16, v200
	v_lshlrev_b32_e32 v201, 16, v201
	v_lshlrev_b32_e32 v202, 16, v202
	v_lshlrev_b32_e32 v203, 16, v203
	v_lshlrev_b32_e32 v204, 16, v204
	v_lshlrev_b32_e32 v205, 16, v205
	s_waitcnt lgkmcnt(0)
	v_pk_fma_f32 v[144:145], v[150:151], v[190:191], v[144:145] op_sel_hi:[0,1,1]
	v_pk_mul_f32 v[190:191], v[150:151], v[190:191] op_sel_hi:[0,1]
	v_pk_fma_f32 v[144:145], v[152:153], v[192:193], v[144:145] op_sel_hi:[0,1,1]
	v_pk_mul_f32 v[192:193], v[152:153], v[192:193] op_sel_hi:[0,1]
	v_pk_fma_f32 v[144:145], v[154:155], v[194:195], v[144:145] op_sel_hi:[0,1,1]
	v_pk_mul_f32 v[194:195], v[154:155], v[194:195] op_sel_hi:[0,1]
	v_pk_fma_f32 v[144:145], v[156:157], v[196:197], v[144:145] op_sel_hi:[0,1,1]
	v_pk_mul_f32 v[196:197], v[156:157], v[196:197] op_sel_hi:[0,1]
	v_pk_fma_f32 v[144:145], v[158:159], v[198:199], v[144:145] op_sel_hi:[0,1,1]
	v_pk_mul_f32 v[198:199], v[158:159], v[198:199] op_sel_hi:[0,1]
	v_pk_fma_f32 v[144:145], v[160:161], v[200:201], v[144:145] op_sel_hi:[0,1,1]
	v_pk_mul_f32 v[200:201], v[160:161], v[200:201] op_sel_hi:[0,1]
	v_pk_fma_f32 v[144:145], v[210:211], v[202:203], v[144:145] op_sel_hi:[0,1,1]
	v_pk_mul_f32 v[202:203], v[210:211], v[202:203] op_sel_hi:[0,1]
	v_pk_fma_f32 v[144:145], v[212:213], v[204:205], v[144:145] op_sel_hi:[0,1,1]
	v_pk_mul_f32 v[204:205], v[212:213], v[204:205] op_sel_hi:[0,1]
	v_cvt_pk_bf16_f32 v128, v190, v192
	v_cvt_pk_bf16_f32 v132, v191, v193
	v_cvt_pk_bf16_f32 v129, v194, v196
	v_cvt_pk_bf16_f32 v133, v195, v197
	v_cvt_pk_bf16_f32 v130, v198, v200
	v_cvt_pk_bf16_f32 v134, v199, v201
	v_cvt_pk_bf16_f32 v131, v202, v204
	v_cvt_pk_bf16_f32 v135, v203, v205
	s_waitcnt vmcnt(24)
	v_perm_b32 v216, v217, v216, s28
	v_perm_b32 v217, v219, v218, s28
	v_perm_b32 v218, v221, v220, s28
	v_perm_b32 v219, v223, v222, s28
	s_nop 1
	v_mfma_f32_32x32x16_bf16 v[96:111], v[216:219], v[128:131], v[96:111]
	v_mfma_f32_32x32x16_bf16 v[112:127], v[216:219], v[132:135], v[112:127]
	s_waitcnt vmcnt(16)
	v_perm_b32 v224, v225, v224, s28
	v_perm_b32 v225, v227, v226, s28
	v_perm_b32 v226, v245, v244, s28
	v_perm_b32 v227, v247, v246, s28
	s_nop 1
	v_mfma_f32_32x32x16_bf16 v[64:79], v[224:227], v[128:131], v[64:79]
	v_mfma_f32_32x32x16_bf16 v[80:95], v[224:227], v[132:135], v[80:95]
	s_waitcnt vmcnt(8)
	v_perm_b32 v248, v249, v248, s28
	v_perm_b32 v249, v251, v250, s28
	v_perm_b32 v250, v253, v252, s28
	v_perm_b32 v251, v155, v153, s28
	s_nop 1
	v_mfma_f32_32x32x16_bf16 v[32:47], v[248:251], v[128:131], v[32:47]
	v_mfma_f32_32x32x16_bf16 v[48:63], v[248:251], v[132:135], v[48:63]
	s_waitcnt vmcnt(0)
	v_perm_b32 v206, v207, v206, s28
	v_perm_b32 v207, v209, v208, s28
	v_perm_b32 v208, v159, v157, s28
	v_perm_b32 v209, v189, v151, s28
	s_nop 1
	v_mfma_f32_32x32x16_bf16 v[0:15], v[206:209], v[128:131], v[0:15]
	v_mfma_f32_32x32x16_bf16 v[16:31], v[206:209], v[132:135], v[16:31]
	s_ashr_i32 s9, s8, 31
	s_lshl_b64 s[2:3], s[8:9], 15
	s_add_u32 s2, s22, s2
	v_lshlrev_b32_e32 v128, 2, v138
	s_addc_u32 s3, s23, s3
	v_lshl_or_b32 v136, v186, 10, v128
	v_lshl_add_u64 v[130:131], s[2:3], 0, v[136:137]
	s_movk_i32 s4, 0x1000
	global_store_dword v136, v96, s[2:3]
	global_store_dword v136, v97, s[2:3] offset:256
	global_store_dword v136, v98, s[2:3] offset:512
	global_store_dword v136, v99, s[2:3] offset:768
	global_store_dword v136, v100, s[2:3] offset:2048
	global_store_dword v136, v101, s[2:3] offset:2304
	global_store_dword v136, v102, s[2:3] offset:2560
	global_store_dword v136, v103, s[2:3] offset:2816
	v_add_co_u32_e64 v96, s[6:7], s4, v130
	s_movk_i32 s4, 0x2000
	s_nop 0
	v_addc_co_u32_e64 v97, s[6:7], 0, v131, s[6:7]
	v_add_co_u32_e64 v98, s[6:7], s4, v130
	v_mov_b32_e32 v129, v137
	s_nop 0
	v_addc_co_u32_e64 v99, s[6:7], 0, v131, s[6:7]
	global_store_dword v[98:99], v104, off offset:-4096
	global_store_dword v[96:97], v105, off offset:256
	global_store_dword v[96:97], v106, off offset:512
	global_store_dword v[96:97], v107, off offset:768
	global_store_dword v[96:97], v108, off offset:2048
	global_store_dword v[96:97], v109, off offset:2304
	global_store_dword v[96:97], v110, off offset:2560
	global_store_dword v[96:97], v111, off offset:2816
	global_store_dword v136, v112, s[2:3] offset:128
	global_store_dword v136, v113, s[2:3] offset:384
	global_store_dword v136, v114, s[2:3] offset:640
	global_store_dword v136, v115, s[2:3] offset:896
	global_store_dword v136, v116, s[2:3] offset:2176
	global_store_dword v136, v117, s[2:3] offset:2432
	global_store_dword v136, v118, s[2:3] offset:2688
	global_store_dword v136, v119, s[2:3] offset:2944
	global_store_dword v[96:97], v120, off offset:128
	global_store_dword v[96:97], v121, off offset:384
	global_store_dword v[96:97], v122, off offset:640
	global_store_dword v[96:97], v123, off offset:896
	global_store_dword v[96:97], v124, off offset:2176
	global_store_dword v[96:97], v125, off offset:2432
	global_store_dword v[96:97], v126, off offset:2688
	global_store_dword v[96:97], v127, off offset:2944
	global_store_dword v[98:99], v64, off
	global_store_dword v[98:99], v65, off offset:256
	global_store_dword v[98:99], v66, off offset:512
	global_store_dword v[98:99], v67, off offset:768
	global_store_dword v[98:99], v68, off offset:2048
	global_store_dword v[98:99], v69, off offset:2304
	global_store_dword v[98:99], v70, off offset:2560
	global_store_dword v[98:99], v71, off offset:2816
	s_movk_i32 s2, 0x3000
	v_add_co_u32_e64 v64, s[6:7], s2, v130
	s_movk_i32 s2, 0x4000
	s_nop 0
	v_addc_co_u32_e64 v65, s[6:7], 0, v131, s[6:7]
	v_add_co_u32_e64 v66, s[6:7], s2, v130
	s_movk_i32 s2, 0x5000
	s_nop 0
	v_addc_co_u32_e64 v67, s[6:7], 0, v131, s[6:7]
	global_store_dword v[66:67], v72, off offset:-4096
	global_store_dword v[64:65], v73, off offset:256
	global_store_dword v[64:65], v74, off offset:512
	global_store_dword v[64:65], v75, off offset:768
	global_store_dword v[64:65], v76, off offset:2048
	global_store_dword v[64:65], v77, off offset:2304
	global_store_dword v[64:65], v78, off offset:2560
	global_store_dword v[64:65], v79, off offset:2816
	global_store_dword v[98:99], v80, off offset:128
	global_store_dword v[98:99], v81, off offset:384
	global_store_dword v[98:99], v82, off offset:640
	global_store_dword v[98:99], v83, off offset:896
	global_store_dword v[98:99], v84, off offset:2176
	global_store_dword v[98:99], v85, off offset:2432
	global_store_dword v[98:99], v86, off offset:2688
	global_store_dword v[98:99], v87, off offset:2944
	global_store_dword v[64:65], v88, off offset:128
	global_store_dword v[64:65], v89, off offset:384
	global_store_dword v[64:65], v90, off offset:640
	global_store_dword v[64:65], v91, off offset:896
	global_store_dword v[64:65], v92, off offset:2176
	global_store_dword v[64:65], v93, off offset:2432
	global_store_dword v[64:65], v94, off offset:2688
	global_store_dword v[64:65], v95, off offset:2944
	global_store_dword v[66:67], v32, off
	global_store_dword v[66:67], v33, off offset:256
	global_store_dword v[66:67], v34, off offset:512
	global_store_dword v[66:67], v35, off offset:768
	global_store_dword v[66:67], v36, off offset:2048
	global_store_dword v[66:67], v37, off offset:2304
	global_store_dword v[66:67], v38, off offset:2560
	global_store_dword v[66:67], v39, off offset:2816
	v_add_co_u32_e64 v32, s[6:7], s2, v130
	s_movk_i32 s2, 0x6000
	s_nop 0
	v_addc_co_u32_e64 v33, s[6:7], 0, v131, s[6:7]
	v_add_co_u32_e64 v34, s[6:7], s2, v130
	s_movk_i32 s2, 0x7000
	s_nop 0
	v_addc_co_u32_e64 v35, s[6:7], 0, v131, s[6:7]
	global_store_dword v[34:35], v40, off offset:-4096
	global_store_dword v[32:33], v41, off offset:256
	global_store_dword v[32:33], v42, off offset:512
	global_store_dword v[32:33], v43, off offset:768
	global_store_dword v[32:33], v44, off offset:2048
	global_store_dword v[32:33], v45, off offset:2304
	global_store_dword v[32:33], v46, off offset:2560
	global_store_dword v[32:33], v47, off offset:2816
	global_store_dword v[66:67], v48, off offset:128
	global_store_dword v[66:67], v49, off offset:384
	global_store_dword v[66:67], v50, off offset:640
	global_store_dword v[66:67], v51, off offset:896
	global_store_dword v[66:67], v52, off offset:2176
	global_store_dword v[66:67], v53, off offset:2432
	global_store_dword v[66:67], v54, off offset:2688
	global_store_dword v[66:67], v55, off offset:2944
	global_store_dword v[32:33], v56, off offset:128
	global_store_dword v[32:33], v57, off offset:384
	global_store_dword v[32:33], v58, off offset:640
	global_store_dword v[32:33], v59, off offset:896
	global_store_dword v[32:33], v60, off offset:2176
	global_store_dword v[32:33], v61, off offset:2432
	global_store_dword v[32:33], v62, off offset:2688
	global_store_dword v[32:33], v63, off offset:2944
	global_store_dword v[34:35], v0, off
	global_store_dword v[34:35], v1, off offset:256
	global_store_dword v[34:35], v2, off offset:512
	global_store_dword v[34:35], v3, off offset:768
	global_store_dword v[34:35], v4, off offset:2048
	global_store_dword v[34:35], v5, off offset:2304
	global_store_dword v[34:35], v6, off offset:2560
	global_store_dword v[34:35], v7, off offset:2816
	ds_bpermute_b32 v2, v185, v144
	v_add_co_u32_e64 v0, s[6:7], s2, v130
	s_lshl_b64 s[2:3], s[8:9], 8
	s_add_u32 s2, s20, s2
	v_addc_co_u32_e64 v1, s[6:7], 0, v131, s[6:7]
	s_addc_u32 s3, s21, s3
	global_store_dword v[0:1], v8, off
	global_store_dword v[0:1], v9, off offset:256
	global_store_dword v[0:1], v10, off offset:512
	global_store_dword v[0:1], v11, off offset:768
	global_store_dword v[0:1], v12, off offset:2048
	global_store_dword v[0:1], v13, off offset:2304
	global_store_dword v[0:1], v14, off offset:2560
	global_store_dword v[0:1], v15, off offset:2816
	global_store_dword v[34:35], v16, off offset:128
	global_store_dword v[34:35], v17, off offset:384
	global_store_dword v[34:35], v18, off offset:640
	global_store_dword v[34:35], v19, off offset:896
	global_store_dword v[34:35], v20, off offset:2176
	global_store_dword v[34:35], v21, off offset:2432
	global_store_dword v[34:35], v22, off offset:2688
	global_store_dword v[34:35], v23, off offset:2944
	global_store_dword v[0:1], v24, off offset:128
	global_store_dword v[0:1], v25, off offset:384
	global_store_dword v[0:1], v26, off offset:640
	global_store_dword v[0:1], v27, off offset:896
	global_store_dword v[0:1], v28, off offset:2176
	global_store_dword v[0:1], v29, off offset:2432
	global_store_dword v[0:1], v30, off offset:2688
	global_store_dword v[0:1], v31, off offset:2944
	v_lshl_add_u64 v[0:1], s[2:3], 0, v[128:129]
	s_and_saveexec_b64 s[2:3], s[0:1]
	s_cbranch_execz .LBB0_507
	s_waitcnt lgkmcnt(0)
	v_add_f32_e32 v2, v144, v2
	global_store_dword v[0:1], v2, off
